# v10 variant: VALU budget per MFMA gap 5 (QK) / 5 (PV)
# baseline (speedup 1.0000x reference)
; __device__ __forceinline__ void finishSM(f32x16& p0, f32x16& p1, float alpha, float& l_reg, bf16x8& pa0, bf16x8& pa1, bf16x8& pa2, bf16x8& pa3) {
; #pragma unroll
;   for (int r = 0; r < 16; ++r) p1[r] = __builtin_amdgcn_exp2f(p1[r]);
;   float ps = 0;
; #pragma unroll
;   for (int r = 0; r < 16; ++r) ps += p0[r];
; #pragma unroll
;   for (int r = 0; r < 16; ++r) ps += p1[r];
;   { auto rr = __builtin_amdgcn_permlane32_swap(__float_as_uint(ps), __float_as_uint(ps), false, false);
;     ps = __uint_as_float(rr[0]) + __uint_as_float(rr[1]); }
;   l_reg = l_reg * alpha + ps;
;     ...
;   PK4(p0, 0, pa0); PK4(p0, 8, pa1); PK4(p1, 0, pa2); PK4(p1, 8, pa3);
;     ...
; }
; __device__ __forceinline__ void qkt(f32x16& p0, f32x16& p1, const char* Ks, const bf16x8* qr, const char* qrl, int r32, int hi) {
;   p0 = f32x16{}; p1 = f32x16{};
; #pragma unroll
;   for (int d0 = 0; d0 < 8; ++d0) { int cb = (d0 * 16 + hi * 8) * 2;
;     bf16x8 b0 = *reinterpret_cast<const bf16x8*>(Ks + KSWZ(r32, cb));
;     bf16x8 b1 = *reinterpret_cast<const bf16x8*>(Ks + KSWZ(32 + r32, cb));
;     p0 = __builtin_amdgcn_mfma_f32_32x32x16_bf16(b0, qr[d0], p0, 0, 0, 0);
;     p1 = __builtin_amdgcn_mfma_f32_32x32x16_bf16(b1, qr[d0], p1, 0, 0, 0); }
; #pragma unroll
;   for (int d0 = 8; d0 < 12; ++d0) { int cb = (d0 * 16 + hi * 8) * 2;
;     bf16x8 b0 = *reinterpret_cast<const bf16x8*>(Ks + KSWZ(r32, cb));
;     bf16x8 b1 = *reinterpret_cast<const bf16x8*>(Ks + KSWZ(32 + r32, cb));
;     bf16x8 qf = *reinterpret_cast<const bf16x8*>(qrl + (((2 * (d0 - 8) + hi) ^ ((r32 >> 1) & 7)) << 4));
;     p0 = __builtin_amdgcn_mfma_f32_32x32x16_bf16(b0, qf, p0, 0, 0, 0);
;     p1 = __builtin_amdgcn_mfma_f32_32x32x16_bf16(b1, qf, p1, 0, 0, 0); }
; }
.LBB0_1151:
	s_sub_i32 s30, s76, 1
	s_cmp_eq_u32 s76, 0
	s_cselect_b32 s30, 2, s30
	s_add_i32 s18, s76, 1
	s_cmp_lg_u32 s76, 2
	s_cselect_b32 s18, s18, 0
	ds_read_b128 v[232:235], v199 offset:36864
	ds_read_b128 v[236:239], v199 offset:49152
	ds_read_b128 v[240:243], v205 offset:36864
	ds_read_b128 v[248:251], v205 offset:49152
	v_exp_f32_e32 v162, v162
	v_add_f32_e32 v211, v225, v228
	v_exp_f32_e32 v163, v163
	v_add_f32_e32 v211, v226, v211
	v_exp_f32_e32 v160, v160
	s_waitcnt lgkmcnt(2)
	v_mfma_f32_32x32x16_bf16 v[80:95], v[232:235], v[124:127], 0
	ds_read_b128 v[232:235], v206 offset:36864
	v_add_f32_e32 v211, v229, v211
	v_exp_f32_e32 v161, v161
	v_add_f32_e32 v211, v227, v211
	v_mfma_f32_32x32x16_bf16 v[64:79], v[236:239], v[124:127], 0
	ds_read_b128 v[236:239], v206 offset:49152
	v_exp_f32_e32 v158, v158
	v_add_f32_e32 v211, v230, v211
	v_exp_f32_e32 v159, v159
	s_waitcnt lgkmcnt(2)
	v_mfma_f32_32x32x16_bf16 v[80:95], v[240:243], v[120:123], v[80:95]
	ds_read_b128 v[240:243], v208 offset:36864
	v_add_f32_e32 v211, v223, v211
	v_exp_f32_e32 v156, v156
	v_add_f32_e32 v211, v224, v211
	v_mfma_f32_32x32x16_bf16 v[64:79], v[248:251], v[120:123], v[64:79]
	ds_read_b128 v[248:251], v208 offset:49152
	v_exp_f32_e32 v157, v157
	v_add_f32_e32 v211, v219, v211
	v_exp_f32_e32 v154, v154
	s_waitcnt lgkmcnt(2)
	v_mfma_f32_32x32x16_bf16 v[80:95], v[232:235], v[116:119], v[80:95]
	ds_read_b128 v[232:235], v207 offset:36864
	v_add_f32_e32 v211, v221, v211
	v_exp_f32_e32 v155, v155
	v_add_f32_e32 v211, v220, v211
	v_mfma_f32_32x32x16_bf16 v[64:79], v[236:239], v[116:119], v[64:79]
	ds_read_b128 v[236:239], v207 offset:49152
	v_exp_f32_e32 v152, v152
	v_add_f32_e32 v211, v222, v211
	v_exp_f32_e32 v153, v153
	s_waitcnt lgkmcnt(2)
	v_mfma_f32_32x32x16_bf16 v[80:95], v[240:243], v[112:115], v[80:95]
	ds_read_b128 v[240:243], v204 offset:36864
	v_add_f32_e32 v211, v215, v211
	v_exp_f32_e32 v150, v150
	v_add_f32_e32 v211, v217, v211
	v_mfma_f32_32x32x16_bf16 v[64:79], v[248:251], v[112:115], v[64:79]
	ds_read_b128 v[248:251], v204 offset:49152
	v_exp_f32_e32 v151, v151
	v_add_f32_e32 v211, v216, v211
	v_exp_f32_e32 v148, v148
	s_waitcnt lgkmcnt(2)
	v_mfma_f32_32x32x16_bf16 v[80:95], v[232:235], v[108:111], v[80:95]
	ds_read_b128 v[232:235], v203 offset:36864
	v_add_f32_e32 v211, v218, v211
	v_exp_f32_e32 v149, v149
	v_add_f32_e32 v212, v162, v163
	v_add_f32_e32 v212, v160, v212
	v_mfma_f32_32x32x16_bf16 v[64:79], v[236:239], v[108:111], v[64:79]
	ds_read_b128 v[236:239], v203 offset:49152
	v_add_f32_e32 v212, v161, v212
	v_add_f32_e32 v212, v158, v212
	v_add_f32_e32 v212, v159, v212
	v_add_f32_e32 v212, v156, v212
	v_add_f32_e32 v212, v157, v212
	s_waitcnt lgkmcnt(2)
	v_mfma_f32_32x32x16_bf16 v[80:95], v[240:243], v[104:107], v[80:95]
	ds_read_b128 v[240:243], v200 offset:36864
	v_add_f32_e32 v212, v154, v212
	v_add_f32_e32 v212, v155, v212
	v_add_f32_e32 v212, v152, v212
	v_add_f32_e32 v212, v153, v212
	v_add_f32_e32 v212, v150, v212
	v_mfma_f32_32x32x16_bf16 v[64:79], v[248:251], v[104:107], v[64:79]
	ds_read_b128 v[248:251], v200 offset:49152
	v_add_f32_e32 v212, v151, v212
	v_add_f32_e32 v212, v148, v212
	v_add_f32_e32 v212, v149, v212
	v_add_f32_e32 v211, v211, v212
	v_mov_b32_e32 v212, v211
	s_lshl_b32 s19, s18, 14
	v_add_u32_e32 v231, s19, v183
	s_waitcnt lgkmcnt(2)
	v_mfma_f32_32x32x16_bf16 v[80:95], v[232:235], v[100:103], v[80:95]
	ds_read_b128 v[232:235], v191 offset:36864
	s_waitcnt vmcnt(0)
	ds_write_b128 v231, v[140:143]
	v_add_u32_e32 v140, s19, v184
	ds_write_b128 v140, v[144:147]
	ds_write_b128 v185, v[136:139] offset:12288
	ds_write_b128 v185, v[132:135] offset:24576
	s_mov_b32 s18, 0xfffa0000
	v_mfma_f32_32x32x16_bf16 v[64:79], v[236:239], v[100:103], v[64:79]
	ds_read_b128 v[236:239], v202 offset:49152
	ds_write_b128 v186, v[128:131] offset:12288
	v_add_co_u32_e32 v128, vcc, s18, v168
	s_mov_b32 s18, 0xfffc0000
	s_nop 0
	v_addc_co_u32_e32 v129, vcc, -1, v169, vcc
	v_add_co_u32_e32 v130, vcc, s18, v168
	s_movk_i32 s18, 0xe000
	s_nop 0
	v_addc_co_u32_e32 v131, vcc, -1, v169, vcc
	s_waitcnt lgkmcnt(7)
; __device__ __forceinline__ void finishSM(f32x16& p0, f32x16& p1, float alpha, float& l_reg, bf16x8& pa0, bf16x8& pa1, bf16x8& pa2, bf16x8& pa3) {
;     ...
;   PK4(p0, 0, pa0); PK4(p0, 8, pa1); PK4(p1, 0, pa2); PK4(p1, 8, pa3);
;     ...
; }
; __device__ __forceinline__ void qkt(f32x16& p0, f32x16& p1, const char* Ks, const bf16x8* qr, const char* qrl, int r32, int hi) {
;   p0 = f32x16{}; p1 = f32x16{};
; #pragma unroll
;   for (int d0 = 0; d0 < 8; ++d0) { int cb = (d0 * 16 + hi * 8) * 2;
;     bf16x8 b0 = *reinterpret_cast<const bf16x8*>(Ks + KSWZ(r32, cb));
;     bf16x8 b1 = *reinterpret_cast<const bf16x8*>(Ks + KSWZ(32 + r32, cb));
;     p0 = __builtin_amdgcn_mfma_f32_32x32x16_bf16(b0, qr[d0], p0, 0, 0, 0);
;     p1 = __builtin_amdgcn_mfma_f32_32x32x16_bf16(b1, qr[d0], p1, 0, 0, 0); }
; #pragma unroll
;   for (int d0 = 8; d0 < 12; ++d0) { int cb = (d0 * 16 + hi * 8) * 2;
;     bf16x8 b0 = *reinterpret_cast<const bf16x8*>(Ks + KSWZ(r32, cb));
;     bf16x8 b1 = *reinterpret_cast<const bf16x8*>(Ks + KSWZ(32 + r32, cb));
;     bf16x8 qf = *reinterpret_cast<const bf16x8*>(qrl + (((2 * (d0 - 8) + hi) ^ ((r32 >> 1) & 7)) << 4));
;     p0 = __builtin_amdgcn_mfma_f32_32x32x16_bf16(b0, qf, p0, 0, 0, 0);
;     p1 = __builtin_amdgcn_mfma_f32_32x32x16_bf16(b1, qf, p1, 0, 0, 0); }
; }
; __device__ __forceinline__ int v_st(int k, int c) { const int kk = (k & ~0xC) | ((k & 4) << 1) | ((k & 8) >> 1); return ((kk >> 3) * 4 + (c >> 5)) * 512 + ((kk & 7) * 32 + (c & 31)) * 2; }
; __device__ __forceinline__ int v_rd_base(int lane) { return ((lane & 3) << 3) | (((lane >> 2) & 3) << 6) | (((lane >> 4) & 1) << 5) | (((lane >> 5) & 1) << 8); }
; template <int OFF> __device__ __forceinline__ s16x4 tr_read(int vb) {
;   s16x4 r; asm volatile("ds_read_b64_tr_b16 %0, %1 offset:%2" : "=&v"(r) : "v"(vb), "i"(OFF) : "memory"); return r;
; }
; template <int D0> __device__ __forceinline__ void pv_one(f32x16& od, int vb, bf16x8 pa0, bf16x8 pa1, bf16x8 pa2, bf16x8 pa3) {
;   const s16x4 l0 = tr_read<v_rd_off(D0, 0, 0)>(vb), h0 = tr_read<v_rd_off(D0, 0, 1)>(vb), l1 = tr_read<v_rd_off(D0, 1, 0)>(vb), h1 = tr_read<v_rd_off(D0, 1, 1)>(vb);
;   const s16x4 l2 = tr_read<v_rd_off(D0, 2, 0)>(vb), h2 = tr_read<v_rd_off(D0, 2, 1)>(vb), l3 = tr_read<v_rd_off(D0, 3, 0)>(vb), h3 = tr_read<v_rd_off(D0, 3, 1)>(vb);
;   asm volatile("s_waitcnt lgkmcnt(0)" ::: "memory"); SBAR();
	v_mfma_f32_32x32x16_bf16 v[80:95], v[240:243], v[96:99], v[80:95]
	ds_read_b128 v[240:243], v182
	global_load_dwordx4 v[140:143], v[128:129], off
	global_load_dwordx4 v[136:139], v[128:129], off offset:-256
	global_load_dwordx4 v[144:147], v[130:131], off
	global_load_dwordx4 v[132:135], v[130:131], off offset:-256
	v_add_co_u32_e32 v128, vcc, s18, v166
	s_nop 1
	v_mfma_f32_32x32x16_bf16 v[64:79], v[248:251], v[96:99], v[64:79]
	ds_read_b128 v[248:251], v198 offset:36864
	v_addc_co_u32_e32 v129, vcc, -1, v167, vcc
	global_load_dwordx4 v[128:131], v[128:129], off
	v_cvt_pk_bf16_f32 v158, v158, v159
	v_cvt_pk_bf16_f32 v159, v156, v157
	v_permlane32_swap_b32_e32 v211, v212
	s_waitcnt lgkmcnt(1)
	v_mfma_f32_32x32x16_bf16 v[80:95], v[232:235], v[240:243], v[80:95]
	ds_read_b128 v[232:235], v201 offset:49152
	v_cvt_pk_bf16_f32 v156, v162, v163
	v_cvt_pk_bf16_f32 v157, v160, v161
	v_cvt_pk_bf16_f32 v160, v154, v155
	v_cvt_pk_bf16_f32 v161, v152, v153
	v_cvt_pk_bf16_f32 v162, v150, v151
	v_mfma_f32_32x32x16_bf16 v[64:79], v[236:239], v[240:243], v[64:79]
	ds_read_b128 v[236:239], v181
	ds_read_b128 v[240:243], v187 offset:36864
	v_cvt_pk_bf16_f32 v163, v148, v149
	v_add_f32_e32 v211, v211, v212
	v_cvt_pk_bf16_f32 v148, v225, v228
	v_cvt_pk_bf16_f32 v149, v226, v229
	v_cvt_pk_bf16_f32 v150, v227, v230
	s_waitcnt lgkmcnt(1)
	v_mfma_f32_32x32x16_bf16 v[80:95], v[248:251], v[236:239], v[80:95]
	ds_read_b128 v[248:251], v189 offset:49152
	v_cvt_pk_bf16_f32 v151, v223, v224
	v_cvt_pk_bf16_f32 v152, v219, v221
	v_cvt_pk_bf16_f32 v153, v220, v222
	v_cvt_pk_bf16_f32 v154, v215, v217
	v_cvt_pk_bf16_f32 v155, v216, v218
	v_mfma_f32_32x32x16_bf16 v[64:79], v[232:235], v[236:239], v[64:79]
	ds_read_b128 v[232:235], v179
	ds_read_b128 v[236:239], v188 offset:36864
	v_fma_f32 v176, v209, v176, v211
	s_waitcnt lgkmcnt(1)
	v_mfma_f32_32x32x16_bf16 v[80:95], v[240:243], v[232:235], v[80:95]
	ds_read_b128 v[240:243], v190 offset:49152
	v_mfma_f32_32x32x16_bf16 v[64:79], v[248:251], v[232:235], v[64:79]
	ds_read_b128 v[248:251], v177
	s_waitcnt lgkmcnt(0)
	v_mfma_f32_32x32x16_bf16 v[80:95], v[236:239], v[248:251], v[80:95]
	v_mfma_f32_32x32x16_bf16 v[64:79], v[240:243], v[248:251], v[64:79]
	s_lshl_b32 s31, s30, 14
	v_add_u32_e32 v180, s31, v178
	ds_read_b64_tr_b16 v[232:233], v180 offset:0
	ds_read_b64_tr_b16 v[234:235], v180 offset:2048
	ds_read_b64_tr_b16 v[236:237], v180 offset:512
	ds_read_b64_tr_b16 v[238:239], v180 offset:2560
	ds_read_b64_tr_b16 v[240:241], v180 offset:1024
	ds_read_b64_tr_b16 v[242:243], v180 offset:3072
	ds_read_b64_tr_b16 v[248:249], v180 offset:1536
	ds_read_b64_tr_b16 v[250:251], v180 offset:3584
	s_nop 3
	v_max3_f32 v194, v80, v81, v82
	v_max3_f32 v195, v64, v65, v66
	v_max3_f32 v194, v194, v83, v84
	v_max3_f32 v195, v195, v67, v68
	v_max3_f32 v194, v194, v85, v86
	s_waitcnt lgkmcnt(4)
	v_mfma_f32_32x32x16_bf16 v[32:47], v[148:151], v[232:235], v[32:47]
	ds_read_b64_tr_b16 v[232:233], v180 offset:4096
	ds_read_b64_tr_b16 v[234:235], v180 offset:6144
	v_max3_f32 v195, v195, v69, v70
	v_max3_f32 v194, v194, v87, v88
	v_max3_f32 v195, v195, v71, v72
	v_max3_f32 v194, v194, v89, v90
	v_max3_f32 v195, v195, v73, v74
	v_mfma_f32_32x32x16_bf16 v[48:63], v[148:151], v[236:239], v[48:63]
	ds_read_b64_tr_b16 v[236:237], v180 offset:4608
	ds_read_b64_tr_b16 v[238:239], v180 offset:6656
	v_max3_f32 v194, v194, v91, v92
	v_max3_f32 v195, v195, v75, v76
	v_max3_f32 v194, v194, v93, v94
	v_max3_f32 v195, v195, v77, v78
	v_max3_f32 v194, v194, v95, v195
	s_waitcnt lgkmcnt(4)
	v_mfma_f32_32x32x16_bf16 v[16:31], v[148:151], v[240:243], v[16:31]
	ds_read_b64_tr_b16 v[240:241], v180 offset:5120
	ds_read_b64_tr_b16 v[242:243], v180 offset:7168
	v_max_f32_e32 v194, v194, v79
	v_mov_b32_e32 v195, v194
	s_nop 1
	v_permlane32_swap_b32_e32 v194, v195
	v_max_f32_e32 v194, v194, v195
	v_mfma_f32_32x32x16_bf16 v[0:15], v[148:151], v[248:251], v[0:15]
	ds_read_b64_tr_b16 v[248:249], v180 offset:5632
	ds_read_b64_tr_b16 v[250:251], v180 offset:7680
	v_sub_f32_e32 v195, v194, v210
	v_cmp_ge_f32_e32 vcc, s15, v195
	s_cmp_eq_u64 vcc, exec
	s_cselect_b64 s[40:41], -1, 0
	s_cbranch_scc1 .Lattn_fast1p
	v_max_f32_e32 v194, v210, v194
	v_sub_f32_e32 v195, v210, v194
	v_mul_f32_e32 v195, 0x3dd53b94, v195
	v_exp_f32_e32 v214, v195
	v_mov_b32_e32 v210, v194
	s_branch .Lattn_join1p

; #define SBAR() __builtin_amdgcn_sched_barrier(0)
; __device__ __forceinline__ void partialSM(f32x16& p0, f32x16& p1, float& m_reg, float& mn, float& alpha) {
;     ...
;   float mnC = -mn * C;
; #pragma unroll
;   for (int r = 0; r < 16; ++r) p0[r] = fmaf(p0[r], C, mnC);
; #pragma unroll
;   for (int r = 0; r < 16; ++r) p1[r] = fmaf(p1[r], C, mnC);
; template <int D0> __device__ __forceinline__ void pv_one(f32x16& od, int vb, bf16x8 pa0, bf16x8 pa1, bf16x8 pa2, bf16x8 pa3) {
;   const s16x4 l0 = tr_read<v_rd_off(D0, 0, 0)>(vb), h0 = tr_read<v_rd_off(D0, 0, 1)>(vb), l1 = tr_read<v_rd_off(D0, 1, 0)>(vb), h1 = tr_read<v_rd_off(D0, 1, 1)>(vb);
;   const s16x4 l2 = tr_read<v_rd_off(D0, 2, 0)>(vb), h2 = tr_read<v_rd_off(D0, 2, 1)>(vb), l3 = tr_read<v_rd_off(D0, 3, 0)>(vb), h3 = tr_read<v_rd_off(D0, 3, 1)>(vb);
;   asm volatile("s_waitcnt lgkmcnt(0)" ::: "memory"); SBAR();
;     ...
;   od = __builtin_amdgcn_mfma_f32_32x32x16_bf16(pa0, PK(l0, h0), od, 0, 0, 0);
;   od = __builtin_amdgcn_mfma_f32_32x32x16_bf16(pa1, PK(l1, h1), od, 0, 0, 0);
;   od = __builtin_amdgcn_mfma_f32_32x32x16_bf16(pa2, PK(l2, h2), od, 0, 0, 0);
;   od = __builtin_amdgcn_mfma_f32_32x32x16_bf16(pa3, PK(l3, h3), od, 0, 0, 0);
;     ...
; }
; __device__ __forceinline__ void pv_d0(f32x16* o, int vb, bf16x8 pa0, bf16x8 pa1, bf16x8 pa2, bf16x8 pa3) {
;   pv_one<0>(o[0], vb, pa0, pa1, pa2, pa3); pv_one<1>(o[1], vb, pa0, pa1, pa2, pa3); pv_one<2>(o[2], vb, pa0, pa1, pa2, pa3); pv_one<3>(o[3], vb, pa0, pa1, pa2, pa3);
.Lattn_join1p:
	s_waitcnt lgkmcnt(4)
	v_mfma_f32_32x32x16_bf16 v[32:47], v[152:155], v[232:235], v[32:47]
	ds_read_b64_tr_b16 v[232:233], v180 offset:8192
	ds_read_b64_tr_b16 v[234:235], v180 offset:10240
	v_mul_f32_e32 v194, 0xbdd53b94, v210
	v_fmamk_f32 v225, v80, 0x3dd53b94, v194
	v_fmamk_f32 v228, v81, 0x3dd53b94, v194
	v_fmamk_f32 v226, v82, 0x3dd53b94, v194
	v_fmamk_f32 v229, v83, 0x3dd53b94, v194
	v_mfma_f32_32x32x16_bf16 v[48:63], v[152:155], v[236:239], v[48:63]
	ds_read_b64_tr_b16 v[236:237], v180 offset:8704
	ds_read_b64_tr_b16 v[238:239], v180 offset:10752
	v_fmamk_f32 v150, v76, 0x3dd53b94, v194
	v_fmamk_f32 v151, v77, 0x3dd53b94, v194
	v_fmamk_f32 v148, v78, 0x3dd53b94, v194
	v_fmamk_f32 v149, v79, 0x3dd53b94, v194
	v_fmamk_f32 v227, v84, 0x3dd53b94, v194
	s_waitcnt lgkmcnt(4)
	v_mfma_f32_32x32x16_bf16 v[16:31], v[152:155], v[240:243], v[16:31]
	ds_read_b64_tr_b16 v[240:241], v180 offset:9216
	ds_read_b64_tr_b16 v[242:243], v180 offset:11264
	v_fmamk_f32 v230, v85, 0x3dd53b94, v194
	v_fmamk_f32 v223, v86, 0x3dd53b94, v194
	v_fmamk_f32 v224, v87, 0x3dd53b94, v194
	v_mfma_f32_32x32x16_bf16 v[0:15], v[152:155], v[248:251], v[0:15]
	ds_read_b64_tr_b16 v[248:249], v180 offset:9728
	ds_read_b64_tr_b16 v[250:251], v180 offset:11776
	v_fmamk_f32 v154, v72, 0x3dd53b94, v194
	v_fmamk_f32 v155, v73, 0x3dd53b94, v194
	v_fmamk_f32 v152, v74, 0x3dd53b94, v194
	v_fmamk_f32 v153, v75, 0x3dd53b94, v194
	v_fmamk_f32 v219, v88, 0x3dd53b94, v194
	s_waitcnt lgkmcnt(4)
	v_mfma_f32_32x32x16_bf16 v[32:47], v[156:159], v[232:235], v[32:47]
	ds_read_b64_tr_b16 v[232:233], v180 offset:12288
	ds_read_b64_tr_b16 v[234:235], v180 offset:14336
	v_fmamk_f32 v221, v89, 0x3dd53b94, v194
	v_fmamk_f32 v220, v90, 0x3dd53b94, v194
	v_fmamk_f32 v222, v91, 0x3dd53b94, v194
	v_mfma_f32_32x32x16_bf16 v[48:63], v[156:159], v[236:239], v[48:63]
	ds_read_b64_tr_b16 v[236:237], v180 offset:12800
	ds_read_b64_tr_b16 v[238:239], v180 offset:14848
	s_waitcnt lgkmcnt(4)
	v_mfma_f32_32x32x16_bf16 v[16:31], v[156:159], v[240:243], v[16:31]
	ds_read_b64_tr_b16 v[240:241], v180 offset:13312
	ds_read_b64_tr_b16 v[242:243], v180 offset:15360
	v_mfma_f32_32x32x16_bf16 v[0:15], v[156:159], v[248:251], v[0:15]
	ds_read_b64_tr_b16 v[248:249], v180 offset:13824
	ds_read_b64_tr_b16 v[250:251], v180 offset:15872
	v_fmamk_f32 v158, v68, 0x3dd53b94, v194
	v_fmamk_f32 v159, v69, 0x3dd53b94, v194
	v_fmamk_f32 v156, v70, 0x3dd53b94, v194
	v_fmamk_f32 v157, v71, 0x3dd53b94, v194
	v_fmamk_f32 v215, v92, 0x3dd53b94, v194
	s_waitcnt lgkmcnt(0)
	s_barrier
	v_mfma_f32_32x32x16_bf16 v[32:47], v[160:163], v[232:235], v[32:47]
	ds_read_b128 v[232:235], v199 offset:12288
	v_fmamk_f32 v217, v93, 0x3dd53b94, v194
	v_fmamk_f32 v216, v94, 0x3dd53b94, v194
	v_fmamk_f32 v218, v95, 0x3dd53b94, v194
	v_mfma_f32_32x32x16_bf16 v[48:63], v[160:163], v[236:239], v[48:63]
	ds_read_b128 v[236:239], v199 offset:24576
	v_mfma_f32_32x32x16_bf16 v[16:31], v[160:163], v[240:243], v[16:31]
	ds_read_b128 v[240:243], v205 offset:12288
	v_mfma_f32_32x32x16_bf16 v[0:15], v[160:163], v[248:251], v[0:15]
	ds_read_b128 v[248:251], v205 offset:24576
	v_fmamk_f32 v162, v64, 0x3dd53b94, v194
	v_fmamk_f32 v163, v65, 0x3dd53b94, v194
	v_fmamk_f32 v160, v66, 0x3dd53b94, v194
	v_fmamk_f32 v161, v67, 0x3dd53b94, v194
	s_and_b64 vcc, exec, s[40:41]
	s_cbranch_vccnz .Lattn_skip_rs1p
	s_and_saveexec_b64 s[18:19], s[38:39]
	ds_write_b32 v175, v214 offset:128
	s_or_b64 exec, exec, s[18:19]
	s_waitcnt lgkmcnt(0)
	v_add_u32_e32 v194, v173, v164
	ds_read_b128 v[64:67], v194 offset:224
	ds_read_b128 v[68:71], v194 offset:192
	ds_read_b128 v[72:75], v194 offset:160
	ds_read_b128 v[76:79], v194 offset:128
	s_waitcnt lgkmcnt(0)
	v_pk_mul_f32 v[44:45], v[44:45], v[64:65]
	v_pk_mul_f32 v[46:47], v[46:47], v[66:67]
	v_pk_mul_f32 v[40:41], v[40:41], v[68:69]
	v_pk_mul_f32 v[42:43], v[42:43], v[70:71]
	v_pk_mul_f32 v[36:37], v[36:37], v[72:73]
	v_pk_mul_f32 v[38:39], v[38:39], v[74:75]
	v_pk_mul_f32 v[32:33], v[32:33], v[76:77]
	v_pk_mul_f32 v[34:35], v[34:35], v[78:79]
	v_pk_mul_f32 v[60:61], v[60:61], v[64:65]
	v_pk_mul_f32 v[62:63], v[62:63], v[66:67]
	v_pk_mul_f32 v[56:57], v[56:57], v[68:69]
	v_pk_mul_f32 v[58:59], v[58:59], v[70:71]
	v_pk_mul_f32 v[52:53], v[52:53], v[72:73]
	v_pk_mul_f32 v[54:55], v[54:55], v[74:75]
	v_pk_mul_f32 v[48:49], v[48:49], v[76:77]
	v_pk_mul_f32 v[50:51], v[50:51], v[78:79]
	v_pk_mul_f32 v[28:29], v[28:29], v[64:65]
	v_pk_mul_f32 v[30:31], v[30:31], v[66:67]
	v_pk_mul_f32 v[24:25], v[24:25], v[68:69]
	v_pk_mul_f32 v[26:27], v[26:27], v[70:71]
	v_pk_mul_f32 v[20:21], v[20:21], v[72:73]
	v_pk_mul_f32 v[22:23], v[22:23], v[74:75]
	v_pk_mul_f32 v[16:17], v[16:17], v[76:77]
	v_pk_mul_f32 v[18:19], v[18:19], v[78:79]
	v_pk_mul_f32 v[12:13], v[12:13], v[64:65]
	v_pk_mul_f32 v[14:15], v[14:15], v[66:67]
	v_pk_mul_f32 v[8:9], v[8:9], v[68:69]
	v_pk_mul_f32 v[10:11], v[10:11], v[70:71]
	v_pk_mul_f32 v[4:5], v[4:5], v[72:73]
	v_pk_mul_f32 v[6:7], v[6:7], v[74:75]
	v_pk_mul_f32 v[0:1], v[0:1], v[76:77]
	v_pk_mul_f32 v[2:3], v[2:3], v[78:79]
; __device__ __forceinline__ void finishSM(f32x16& p0, f32x16& p1, float alpha, float& l_reg, bf16x8& pa0, bf16x8& pa1, bf16x8& pa2, bf16x8& pa3) {
; #pragma unroll
;   for (int r = 0; r < 16; ++r) p1[r] = __builtin_amdgcn_exp2f(p1[r]);
;   float ps = 0;
; #pragma unroll
;   for (int r = 0; r < 16; ++r) ps += p0[r];
; #pragma unroll
;   for (int r = 0; r < 16; ++r) ps += p1[r];
;   { auto rr = __builtin_amdgcn_permlane32_swap(__float_as_uint(ps), __float_as_uint(ps), false, false);
;     ps = __uint_as_float(rr[0]) + __uint_as_float(rr[1]); }
;   l_reg = l_reg * alpha + ps;
;     ...
;   PK4(p0, 0, pa0); PK4(p0, 8, pa1); PK4(p1, 0, pa2); PK4(p1, 8, pa3);
;     ...
; }
; __device__ __forceinline__ void qkt(f32x16& p0, f32x16& p1, const char* Ks, const bf16x8* qr, const char* qrl, int r32, int hi) {
;   p0 = f32x16{}; p1 = f32x16{};
; #pragma unroll
;   for (int d0 = 0; d0 < 8; ++d0) { int cb = (d0 * 16 + hi * 8) * 2;
;     bf16x8 b0 = *reinterpret_cast<const bf16x8*>(Ks + KSWZ(r32, cb));
;     bf16x8 b1 = *reinterpret_cast<const bf16x8*>(Ks + KSWZ(32 + r32, cb));
;     p0 = __builtin_amdgcn_mfma_f32_32x32x16_bf16(b0, qr[d0], p0, 0, 0, 0);
;     p1 = __builtin_amdgcn_mfma_f32_32x32x16_bf16(b1, qr[d0], p1, 0, 0, 0); }
; #pragma unroll
;   for (int d0 = 8; d0 < 12; ++d0) { int cb = (d0 * 16 + hi * 8) * 2;
;     bf16x8 b0 = *reinterpret_cast<const bf16x8*>(Ks + KSWZ(r32, cb));
;     bf16x8 b1 = *reinterpret_cast<const bf16x8*>(Ks + KSWZ(32 + r32, cb));
;     bf16x8 qf = *reinterpret_cast<const bf16x8*>(qrl + (((2 * (d0 - 8) + hi) ^ ((r32 >> 1) & 7)) << 4));
;     p0 = __builtin_amdgcn_mfma_f32_32x32x16_bf16(b0, qf, p0, 0, 0, 0);
;     p1 = __builtin_amdgcn_mfma_f32_32x32x16_bf16(b1, qf, p1, 0, 0, 0); }
; }
.Lattn_skip_rs1p:
	v_exp_f32_e32 v225, v225
	v_exp_f32_e32 v228, v228
	v_exp_f32_e32 v226, v226
	v_add_f32_e32 v211, v225, v228
	s_waitcnt lgkmcnt(2)
	v_mfma_f32_32x32x16_bf16 v[80:95], v[232:235], v[124:127], 0
	ds_read_b128 v[232:235], v206 offset:12288
	v_exp_f32_e32 v229, v229
	v_add_f32_e32 v211, v226, v211
	v_exp_f32_e32 v227, v227
	v_mfma_f32_32x32x16_bf16 v[64:79], v[236:239], v[124:127], 0
	ds_read_b128 v[236:239], v206 offset:24576
	v_add_f32_e32 v211, v229, v211
	v_exp_f32_e32 v230, v230
	v_add_f32_e32 v211, v227, v211
	s_waitcnt lgkmcnt(2)
	v_mfma_f32_32x32x16_bf16 v[80:95], v[240:243], v[120:123], v[80:95]
	ds_read_b128 v[240:243], v208 offset:12288
	v_exp_f32_e32 v223, v223
	v_add_f32_e32 v211, v230, v211
	v_exp_f32_e32 v224, v224
	v_mfma_f32_32x32x16_bf16 v[64:79], v[248:251], v[120:123], v[64:79]
	ds_read_b128 v[248:251], v208 offset:24576
	v_add_f32_e32 v211, v223, v211
	v_exp_f32_e32 v219, v219
	v_add_f32_e32 v211, v224, v211
	s_waitcnt lgkmcnt(2)
	v_mfma_f32_32x32x16_bf16 v[80:95], v[232:235], v[116:119], v[80:95]
	ds_read_b128 v[232:235], v207 offset:12288
	v_exp_f32_e32 v221, v221
	v_add_f32_e32 v211, v219, v211
	v_exp_f32_e32 v220, v220
	v_mfma_f32_32x32x16_bf16 v[64:79], v[236:239], v[116:119], v[64:79]
	ds_read_b128 v[236:239], v207 offset:24576
	v_add_f32_e32 v211, v221, v211
	v_exp_f32_e32 v222, v222
	v_add_f32_e32 v211, v220, v211
	s_waitcnt lgkmcnt(2)
	v_mfma_f32_32x32x16_bf16 v[80:95], v[240:243], v[112:115], v[80:95]
	ds_read_b128 v[240:243], v204 offset:12288
	v_exp_f32_e32 v215, v215
	v_add_f32_e32 v211, v222, v211
	v_exp_f32_e32 v217, v217
	v_mfma_f32_32x32x16_bf16 v[64:79], v[248:251], v[112:115], v[64:79]
	ds_read_b128 v[248:251], v204 offset:24576
	v_add_f32_e32 v211, v215, v211
	v_exp_f32_e32 v216, v216
	v_add_f32_e32 v211, v217, v211
	s_waitcnt lgkmcnt(2)
	v_mfma_f32_32x32x16_bf16 v[80:95], v[232:235], v[108:111], v[80:95]
	ds_read_b128 v[232:235], v203 offset:12288
	v_exp_f32_e32 v218, v218
	v_add_f32_e32 v211, v216, v211
	v_exp_f32_e32 v162, v162
	v_mfma_f32_32x32x16_bf16 v[64:79], v[236:239], v[108:111], v[64:79]
	ds_read_b128 v[236:239], v203 offset:24576
	v_add_f32_e32 v211, v218, v211
	v_exp_f32_e32 v163, v163
	v_exp_f32_e32 v160, v160
	s_waitcnt lgkmcnt(2)
	v_mfma_f32_32x32x16_bf16 v[80:95], v[240:243], v[104:107], v[80:95]
	ds_read_b128 v[240:243], v200 offset:12288
	v_exp_f32_e32 v161, v161
	v_exp_f32_e32 v158, v158
	v_mfma_f32_32x32x16_bf16 v[64:79], v[248:251], v[104:107], v[64:79]
	ds_read_b128 v[248:251], v200 offset:24576
	v_exp_f32_e32 v159, v159
	v_exp_f32_e32 v156, v156
	s_waitcnt lgkmcnt(2)
	v_mfma_f32_32x32x16_bf16 v[80:95], v[232:235], v[100:103], v[80:95]
	ds_read_b128 v[232:235], v191 offset:12288
	v_exp_f32_e32 v157, v157
	v_exp_f32_e32 v154, v154
	v_mfma_f32_32x32x16_bf16 v[64:79], v[236:239], v[100:103], v[64:79]
	ds_read_b128 v[236:239], v202 offset:24576
	v_exp_f32_e32 v155, v155
	v_exp_f32_e32 v152, v152
	s_waitcnt lgkmcnt(2)
	v_mfma_f32_32x32x16_bf16 v[80:95], v[240:243], v[96:99], v[80:95]
	ds_read_b128 v[240:243], v182
	v_exp_f32_e32 v153, v153
	v_exp_f32_e32 v150, v150
	v_mfma_f32_32x32x16_bf16 v[64:79], v[248:251], v[96:99], v[64:79]
	ds_read_b128 v[248:251], v198 offset:12288
	v_exp_f32_e32 v151, v151
	v_exp_f32_e32 v148, v148
	s_waitcnt lgkmcnt(1)
	v_mfma_f32_32x32x16_bf16 v[80:95], v[232:235], v[240:243], v[80:95]
	ds_read_b128 v[232:235], v201 offset:24576
	v_exp_f32_e32 v149, v149
	v_add_f32_e32 v212, v162, v163
	v_add_f32_e32 v212, v160, v212
	v_add_f32_e32 v212, v161, v212
	v_mfma_f32_32x32x16_bf16 v[64:79], v[236:239], v[240:243], v[64:79]
	ds_read_b128 v[236:239], v181
	ds_read_b128 v[240:243], v187 offset:12288
	v_add_f32_e32 v212, v158, v212
	v_add_f32_e32 v212, v159, v212
	v_add_f32_e32 v212, v156, v212
	v_add_f32_e32 v212, v157, v212
	v_add_f32_e32 v212, v154, v212
	s_waitcnt lgkmcnt(1)
	v_mfma_f32_32x32x16_bf16 v[80:95], v[248:251], v[236:239], v[80:95]
	ds_read_b128 v[248:251], v189 offset:24576
	v_add_f32_e32 v212, v155, v212
	v_add_f32_e32 v212, v152, v212
	v_add_f32_e32 v212, v153, v212
	v_add_f32_e32 v212, v150, v212
	v_add_f32_e32 v212, v151, v212
	v_mfma_f32_32x32x16_bf16 v[64:79], v[232:235], v[236:239], v[64:79]
	ds_read_b128 v[232:235], v179
	ds_read_b128 v[236:239], v188 offset:12288
	v_add_f32_e32 v212, v148, v212
	v_add_f32_e32 v212, v149, v212
	v_add_f32_e32 v211, v211, v212
	v_mov_b32_e32 v212, v211
	v_add_u32_e32 v194, s31, v183
	s_waitcnt vmcnt(4)
	s_waitcnt lgkmcnt(1)
	v_mfma_f32_32x32x16_bf16 v[80:95], v[240:243], v[232:235], v[80:95]
	ds_read_b128 v[240:243], v190 offset:24576
	ds_write_b128 v194, v[140:143]
	v_add_u32_e32 v194, s31, v184
	s_add_i32 s73, s73, 2
	s_cmp_ge_u32 s73, s45
	s_waitcnt vmcnt(2)
	ds_write_b128 v194, v[144:147]
	s_cselect_b64 s[28:29], -1, 0
	ds_write_b128 v185, v[136:139] offset:36864
	s_waitcnt vmcnt(1)
	v_mfma_f32_32x32x16_bf16 v[64:79], v[248:251], v[232:235], v[64:79]
	ds_read_b128 v[248:251], v177
	ds_write_b128 v185, v[132:135] offset:49152
	s_and_b64 vcc, exec, s[28:29]
	s_waitcnt vmcnt(0)
	ds_write_b128 v186, v[128:131] offset:36864
	s_waitcnt lgkmcnt(2)
	v_mfma_f32_32x32x16_bf16 v[80:95], v[236:239], v[248:251], v[80:95]
	v_mfma_f32_32x32x16_bf16 v[64:79], v[240:243], v[248:251], v[64:79]
	v_lshl_add_u32 v231, s76, 14, v178
	ds_read_b64_tr_b16 v[232:233], v231 offset:0
	ds_read_b64_tr_b16 v[234:235], v231 offset:2048
	ds_read_b64_tr_b16 v[236:237], v231 offset:512
	ds_read_b64_tr_b16 v[238:239], v231 offset:2560
	ds_read_b64_tr_b16 v[240:241], v231 offset:1024
	ds_read_b64_tr_b16 v[242:243], v231 offset:3072
	ds_read_b64_tr_b16 v[248:249], v231 offset:1536
	ds_read_b64_tr_b16 v[250:251], v231 offset:3584
	s_cbranch_vccnz .Lattn_noloadp
	v_add_co_u32_e32 v128, vcc, 0xfffe0000, v168
	s_nop 1
	v_addc_co_u32_e32 v129, vcc, -1, v169, vcc
	global_load_dwordx4 v[140:143], v[128:129], off
	global_load_dwordx4 v[136:139], v[128:129], off offset:-256
	global_load_dwordx4 v[144:147], v[168:169], off
	global_load_dwordx4 v[132:135], v[168:169], off offset:-256
	s_nop 0
	global_load_dwordx4 v[128:131], v[166:167], off
; #define SBAR() __builtin_amdgcn_sched_barrier(0)
; __device__ __forceinline__ void partialSM(f32x16& p0, f32x16& p1, float& m_reg, float& mn, float& alpha) {
;   constexpr float C = SCALE * 1.4426950408889634f;
;   float pmax = p0[0];
; #pragma unroll
;   for (int r = 1; r < 16; ++r) pmax = fmaxf(pmax, p0[r]);
; #pragma unroll
;   for (int r = 0; r < 16; ++r) pmax = fmaxf(pmax, p1[r]);
;   { auto rr = __builtin_amdgcn_permlane32_swap(__float_as_uint(pmax), __float_as_uint(pmax), false, false);
;     pmax = fmaxf(__uint_as_float(rr[0]), __uint_as_float(rr[1])); }
;   if (__builtin_expect(__all(pmax - m_reg <= THR / SCALE), 1)) { mn = m_reg; alpha = 1.f; }
;   else { mn = fmaxf(m_reg, pmax); alpha = __builtin_amdgcn_exp2f((m_reg - mn) * C); m_reg = mn; }
;   float mnC = -mn * C;
; #pragma unroll
;   for (int r = 0; r < 16; ++r) p0[r] = fmaf(p0[r], C, mnC);
; #pragma unroll
;   for (int r = 0; r < 16; ++r) p1[r] = fmaf(p1[r], C, mnC);
; #pragma unroll
;   for (int r = 0; r < 16; ++r) p0[r] = __builtin_amdgcn_exp2f(p0[r]);
; }
; __device__ __forceinline__ void finishSM(f32x16& p0, f32x16& p1, float alpha, float& l_reg, bf16x8& pa0, bf16x8& pa1, bf16x8& pa2, bf16x8& pa3) {
; #pragma unroll
;   for (int r = 0; r < 16; ++r) p1[r] = __builtin_amdgcn_exp2f(p1[r]);
;   float ps = 0;
; #pragma unroll
;   for (int r = 0; r < 16; ++r) ps += p0[r];
; #pragma unroll
;   for (int r = 0; r < 16; ++r) ps += p1[r];
;   { auto rr = __builtin_amdgcn_permlane32_swap(__float_as_uint(ps), __float_as_uint(ps), false, false);
;     ps = __uint_as_float(rr[0]) + __uint_as_float(rr[1]); }
;   l_reg = l_reg * alpha + ps;
;     ...
;   PK4(p0, 0, pa0); PK4(p0, 8, pa1); PK4(p1, 0, pa2); PK4(p1, 8, pa3);
; template <int D0> __device__ __forceinline__ void pv_one(f32x16& od, int vb, bf16x8 pa0, bf16x8 pa1, bf16x8 pa2, bf16x8 pa3) {
;   const s16x4 l0 = tr_read<v_rd_off(D0, 0, 0)>(vb), h0 = tr_read<v_rd_off(D0, 0, 1)>(vb), l1 = tr_read<v_rd_off(D0, 1, 0)>(vb), h1 = tr_read<v_rd_off(D0, 1, 1)>(vb);
;   const s16x4 l2 = tr_read<v_rd_off(D0, 2, 0)>(vb), h2 = tr_read<v_rd_off(D0, 2, 1)>(vb), l3 = tr_read<v_rd_off(D0, 3, 0)>(vb), h3 = tr_read<v_rd_off(D0, 3, 1)>(vb);
;   asm volatile("s_waitcnt lgkmcnt(0)" ::: "memory"); SBAR();
;     ...
;   od = __builtin_amdgcn_mfma_f32_32x32x16_bf16(pa0, PK(l0, h0), od, 0, 0, 0);
;   od = __builtin_amdgcn_mfma_f32_32x32x16_bf16(pa1, PK(l1, h1), od, 0, 0, 0);
.Lattn_noloadp:
	v_cvt_pk_bf16_f32 v158, v158, v159
	v_cvt_pk_bf16_f32 v159, v156, v157
	v_permlane32_swap_b32_e32 v211, v212
	v_cvt_pk_bf16_f32 v156, v162, v163
	v_cvt_pk_bf16_f32 v157, v160, v161
	v_cvt_pk_bf16_f32 v160, v154, v155
	v_cvt_pk_bf16_f32 v161, v152, v153
	v_cvt_pk_bf16_f32 v162, v150, v151
	v_cvt_pk_bf16_f32 v163, v148, v149
	v_add_f32_e32 v211, v211, v212
	v_cvt_pk_bf16_f32 v148, v225, v228
	v_cvt_pk_bf16_f32 v149, v226, v229
	v_cvt_pk_bf16_f32 v150, v227, v230
	v_cvt_pk_bf16_f32 v151, v223, v224
	v_cvt_pk_bf16_f32 v152, v219, v221
	v_cvt_pk_bf16_f32 v153, v220, v222
	v_cvt_pk_bf16_f32 v154, v215, v217
	v_cvt_pk_bf16_f32 v155, v216, v218
	v_fma_f32 v176, v214, v176, v211
	s_nop 3
	v_max3_f32 v194, v80, v81, v82
	v_max3_f32 v195, v64, v65, v66
	v_max3_f32 v194, v194, v83, v84
	v_max3_f32 v195, v195, v67, v68
	v_max3_f32 v194, v194, v85, v86
	s_waitcnt lgkmcnt(4)
	v_mfma_f32_32x32x16_bf16 v[32:47], v[148:151], v[232:235], v[32:47]
	ds_read_b64_tr_b16 v[232:233], v231 offset:4096
	ds_read_b64_tr_b16 v[234:235], v231 offset:6144
	v_max3_f32 v195, v195, v69, v70
	v_max3_f32 v194, v194, v87, v88
	v_max3_f32 v195, v195, v71, v72
	v_max3_f32 v194, v194, v89, v90
	v_max3_f32 v195, v195, v73, v74
	v_mfma_f32_32x32x16_bf16 v[48:63], v[148:151], v[236:239], v[48:63]
	ds_read_b64_tr_b16 v[236:237], v231 offset:4608
	ds_read_b64_tr_b16 v[238:239], v231 offset:6656
	v_max3_f32 v194, v194, v91, v92
	v_max3_f32 v195, v195, v75, v76
	v_max3_f32 v194, v194, v93, v94
	v_max3_f32 v195, v195, v77, v78
	v_max3_f32 v194, v194, v95, v195
	s_waitcnt lgkmcnt(4)
	v_mfma_f32_32x32x16_bf16 v[16:31], v[148:151], v[240:243], v[16:31]
	ds_read_b64_tr_b16 v[240:241], v231 offset:5120
	ds_read_b64_tr_b16 v[242:243], v231 offset:7168
	v_max_f32_e32 v194, v194, v79
	v_mov_b32_e32 v195, v194
	s_nop 1
	v_permlane32_swap_b32_e32 v194, v195
	v_max_f32_e32 v194, v194, v195
	v_mfma_f32_32x32x16_bf16 v[0:15], v[148:151], v[248:251], v[0:15]
	ds_read_b64_tr_b16 v[248:249], v231 offset:5632
	ds_read_b64_tr_b16 v[250:251], v231 offset:7680
	v_sub_f32_e32 v195, v194, v210
	v_cmp_ge_f32_e32 vcc, s15, v195
	s_cmp_eq_u64 vcc, exec
	s_cselect_b64 s[40:41], -1, 0
	s_cbranch_scc1 .Lattn_fast2p
	v_max_f32_e32 v194, v210, v194
	v_sub_f32_e32 v195, v210, v194
	v_mul_f32_e32 v195, 0x3dd53b94, v195
	v_exp_f32_e32 v213, v195
	v_mov_b32_e32 v210, v194
	s_branch .Lattn_join2p

; __device__ __forceinline__ void partialSM(f32x16& p0, f32x16& p1, float& m_reg, float& mn, float& alpha) {
;     ...
;   float mnC = -mn * C;
; #pragma unroll
;   for (int r = 0; r < 16; ++r) p0[r] = fmaf(p0[r], C, mnC);
; #pragma unroll
;   for (int r = 0; r < 16; ++r) p1[r] = fmaf(p1[r], C, mnC);
; template <int D0> __device__ __forceinline__ void pv_one(f32x16& od, int vb, bf16x8 pa0, bf16x8 pa1, bf16x8 pa2, bf16x8 pa3) {
;   const s16x4 l0 = tr_read<v_rd_off(D0, 0, 0)>(vb), h0 = tr_read<v_rd_off(D0, 0, 1)>(vb), l1 = tr_read<v_rd_off(D0, 1, 0)>(vb), h1 = tr_read<v_rd_off(D0, 1, 1)>(vb);
;   const s16x4 l2 = tr_read<v_rd_off(D0, 2, 0)>(vb), h2 = tr_read<v_rd_off(D0, 2, 1)>(vb), l3 = tr_read<v_rd_off(D0, 3, 0)>(vb), h3 = tr_read<v_rd_off(D0, 3, 1)>(vb);
;   asm volatile("s_waitcnt lgkmcnt(0)" ::: "memory"); SBAR();
;     ...
;   od = __builtin_amdgcn_mfma_f32_32x32x16_bf16(pa0, PK(l0, h0), od, 0, 0, 0);
;   od = __builtin_amdgcn_mfma_f32_32x32x16_bf16(pa1, PK(l1, h1), od, 0, 0, 0);
;   od = __builtin_amdgcn_mfma_f32_32x32x16_bf16(pa2, PK(l2, h2), od, 0, 0, 0);
;   od = __builtin_amdgcn_mfma_f32_32x32x16_bf16(pa3, PK(l3, h3), od, 0, 0, 0);
;     ...
; }
; __device__ __forceinline__ void pv_d0(f32x16* o, int vb, bf16x8 pa0, bf16x8 pa1, bf16x8 pa2, bf16x8 pa3) {
;   pv_one<0>(o[0], vb, pa0, pa1, pa2, pa3); pv_one<1>(o[1], vb, pa0, pa1, pa2, pa3); pv_one<2>(o[2], vb, pa0, pa1, pa2, pa3); pv_one<3>(o[3], vb, pa0, pa1, pa2, pa3);
; }
; __device__ __forceinline__ void attn_unit(const bf16_t* __restrict__ Qb, const bf16_t* __restrict__ Kn, const bf16_t* __restrict__ Vh, const bf16_t* __restrict__ Kr,
;                                           bf16_t* GO, int seq, char* lds, const int tid) {
;   const int wid = tid >> 6, lane = tid & 63, r32 = lane & 31, hi = lane >> 5;
;   char* V_lds = lds; char* K_lds = lds + 3 * SHM_V;
;   float* ws = (float*)(lds + 3 * SHM_V + 3 * SHM_K) + wid * 64; float* li_l = ws; float* al_l = ws + 32;
;   if (wid < 4) __builtin_amdgcn_s_setprio(2); else __builtin_amdgcn_s_setprio(0);
;   float m_reg = -1e30f, l_reg = 0; f32x16 o[4] = {}; bf16x8 qr[8];
;   char* qrl = lds + 3 * SHM_V + 3 * SHM_K + NW * 64 * 4 + wid * 4096 + r32 * 128;
;   const bf16_t* Qw = Qb + (long)(wid * QBLK + r32) * LDQ + hi * 8;
; #pragma unroll
;   for (int d0 = 0; d0 < 8; ++d0) qr[d0] = *reinterpret_cast<const bf16x8*>(Qw + d0 * 16);
; #pragma unroll
.Lattn_join2p:
	s_waitcnt lgkmcnt(4)
	v_mfma_f32_32x32x16_bf16 v[32:47], v[152:155], v[232:235], v[32:47]
	ds_read_b64_tr_b16 v[232:233], v231 offset:8192
	ds_read_b64_tr_b16 v[234:235], v231 offset:10240
	v_mul_f32_e32 v194, 0xbdd53b94, v210
	v_fmamk_f32 v225, v80, 0x3dd53b94, v194
	v_fmamk_f32 v228, v81, 0x3dd53b94, v194
	v_fmamk_f32 v226, v82, 0x3dd53b94, v194
	v_fmamk_f32 v229, v83, 0x3dd53b94, v194
	v_mfma_f32_32x32x16_bf16 v[48:63], v[152:155], v[236:239], v[48:63]
	ds_read_b64_tr_b16 v[236:237], v231 offset:8704
	ds_read_b64_tr_b16 v[238:239], v231 offset:10752
	v_fmamk_f32 v150, v76, 0x3dd53b94, v194
	v_fmamk_f32 v151, v77, 0x3dd53b94, v194
	v_fmamk_f32 v148, v78, 0x3dd53b94, v194
	v_fmamk_f32 v149, v79, 0x3dd53b94, v194
	v_fmamk_f32 v227, v84, 0x3dd53b94, v194
	s_waitcnt lgkmcnt(4)
	v_mfma_f32_32x32x16_bf16 v[16:31], v[152:155], v[240:243], v[16:31]
	ds_read_b64_tr_b16 v[240:241], v231 offset:9216
	ds_read_b64_tr_b16 v[242:243], v231 offset:11264
	v_fmamk_f32 v230, v85, 0x3dd53b94, v194
	v_fmamk_f32 v223, v86, 0x3dd53b94, v194
	v_fmamk_f32 v224, v87, 0x3dd53b94, v194
	v_mfma_f32_32x32x16_bf16 v[0:15], v[152:155], v[248:251], v[0:15]
	ds_read_b64_tr_b16 v[248:249], v231 offset:9728
	ds_read_b64_tr_b16 v[250:251], v231 offset:11776
	v_fmamk_f32 v154, v72, 0x3dd53b94, v194
	v_fmamk_f32 v155, v73, 0x3dd53b94, v194
	v_fmamk_f32 v152, v74, 0x3dd53b94, v194
	v_fmamk_f32 v153, v75, 0x3dd53b94, v194
	v_fmamk_f32 v219, v88, 0x3dd53b94, v194
	s_waitcnt lgkmcnt(4)
	v_mfma_f32_32x32x16_bf16 v[32:47], v[156:159], v[232:235], v[32:47]
	ds_read_b64_tr_b16 v[232:233], v231 offset:12288
	ds_read_b64_tr_b16 v[234:235], v231 offset:14336
	v_fmamk_f32 v221, v89, 0x3dd53b94, v194
	v_fmamk_f32 v220, v90, 0x3dd53b94, v194
	v_fmamk_f32 v222, v91, 0x3dd53b94, v194
	v_mfma_f32_32x32x16_bf16 v[48:63], v[156:159], v[236:239], v[48:63]
	ds_read_b64_tr_b16 v[236:237], v231 offset:12800
	ds_read_b64_tr_b16 v[238:239], v231 offset:14848
	s_waitcnt lgkmcnt(4)
	v_mfma_f32_32x32x16_bf16 v[16:31], v[156:159], v[240:243], v[16:31]
	ds_read_b64_tr_b16 v[240:241], v231 offset:13312
	ds_read_b64_tr_b16 v[242:243], v231 offset:15360
	v_mfma_f32_32x32x16_bf16 v[0:15], v[156:159], v[248:251], v[0:15]
	ds_read_b64_tr_b16 v[248:249], v231 offset:13824
	ds_read_b64_tr_b16 v[250:251], v231 offset:15872
	v_fmamk_f32 v158, v68, 0x3dd53b94, v194
	v_fmamk_f32 v159, v69, 0x3dd53b94, v194
	v_fmamk_f32 v156, v70, 0x3dd53b94, v194
	v_fmamk_f32 v157, v71, 0x3dd53b94, v194
	v_fmamk_f32 v215, v92, 0x3dd53b94, v194
	s_waitcnt lgkmcnt(0)
	s_barrier
	v_mfma_f32_32x32x16_bf16 v[32:47], v[160:163], v[232:235], v[32:47]
	ds_read_b128 v[232:235], v199 offset:36864
	v_fmamk_f32 v217, v93, 0x3dd53b94, v194
	v_fmamk_f32 v216, v94, 0x3dd53b94, v194
	v_fmamk_f32 v218, v95, 0x3dd53b94, v194
	v_mfma_f32_32x32x16_bf16 v[48:63], v[160:163], v[236:239], v[48:63]
	ds_read_b128 v[236:239], v199 offset:49152
	v_mfma_f32_32x32x16_bf16 v[16:31], v[160:163], v[240:243], v[16:31]
	ds_read_b128 v[240:243], v205 offset:36864
	v_mfma_f32_32x32x16_bf16 v[0:15], v[160:163], v[248:251], v[0:15]
	ds_read_b128 v[248:251], v205 offset:49152
	v_fmamk_f32 v162, v64, 0x3dd53b94, v194
	v_fmamk_f32 v163, v65, 0x3dd53b94, v194
	v_fmamk_f32 v160, v66, 0x3dd53b94, v194
	v_fmamk_f32 v161, v67, 0x3dd53b94, v194
	s_and_b64 vcc, exec, s[40:41]
	s_cbranch_vccnz .Lattn_skip_rs2p
	s_and_saveexec_b64 s[18:19], s[38:39]
	ds_write_b32 v175, v213 offset:128
	s_or_b64 exec, exec, s[18:19]
	s_waitcnt lgkmcnt(0)
	v_add_u32_e32 v194, v173, v164
	ds_read_b128 v[64:67], v194 offset:224
	ds_read_b128 v[68:71], v194 offset:192
	ds_read_b128 v[72:75], v194 offset:160
	ds_read_b128 v[76:79], v194 offset:128
	s_waitcnt lgkmcnt(0)
	v_pk_mul_f32 v[44:45], v[44:45], v[64:65]
	v_pk_mul_f32 v[46:47], v[46:47], v[66:67]
	v_pk_mul_f32 v[40:41], v[40:41], v[68:69]
	v_pk_mul_f32 v[42:43], v[42:43], v[70:71]
	v_pk_mul_f32 v[36:37], v[36:37], v[72:73]
	v_pk_mul_f32 v[38:39], v[38:39], v[74:75]
	v_pk_mul_f32 v[32:33], v[32:33], v[76:77]
	v_pk_mul_f32 v[34:35], v[34:35], v[78:79]
	v_pk_mul_f32 v[60:61], v[60:61], v[64:65]
	v_pk_mul_f32 v[62:63], v[62:63], v[66:67]
	v_pk_mul_f32 v[56:57], v[56:57], v[68:69]
	v_pk_mul_f32 v[58:59], v[58:59], v[70:71]
	v_pk_mul_f32 v[52:53], v[52:53], v[72:73]
	v_pk_mul_f32 v[54:55], v[54:55], v[74:75]
	v_pk_mul_f32 v[48:49], v[48:49], v[76:77]
	v_pk_mul_f32 v[50:51], v[50:51], v[78:79]
	v_pk_mul_f32 v[28:29], v[28:29], v[64:65]
	v_pk_mul_f32 v[30:31], v[30:31], v[66:67]
	v_pk_mul_f32 v[24:25], v[24:25], v[68:69]
	v_pk_mul_f32 v[26:27], v[26:27], v[70:71]
	v_pk_mul_f32 v[20:21], v[20:21], v[72:73]
	v_pk_mul_f32 v[22:23], v[22:23], v[74:75]
	v_pk_mul_f32 v[16:17], v[16:17], v[76:77]
	v_pk_mul_f32 v[18:19], v[18:19], v[78:79]
	v_pk_mul_f32 v[12:13], v[12:13], v[64:65]
	v_pk_mul_f32 v[14:15], v[14:15], v[66:67]
	v_pk_mul_f32 v[8:9], v[8:9], v[68:69]
	v_pk_mul_f32 v[10:11], v[10:11], v[70:71]
	v_pk_mul_f32 v[4:5], v[4:5], v[72:73]
	v_pk_mul_f32 v[6:7], v[6:7], v[74:75]
	v_pk_mul_f32 v[0:1], v[0:1], v[76:77]
	v_pk_mul_f32 v[2:3], v[2:3], v[78:79]

; __device__ __forceinline__ void partialSM(f32x16& p0, f32x16& p1, float& m_reg, float& mn, float& alpha) {
;     ...
;   for (int r = 0; r < 16; ++r) p0[r] = __builtin_amdgcn_exp2f(p0[r]);
; }
; __device__ __forceinline__ void finishSM(f32x16& p0, f32x16& p1, float alpha, float& l_reg, bf16x8& pa0, bf16x8& pa1, bf16x8& pa2, bf16x8& pa3) {
; #pragma unroll
;   for (int r = 0; r < 16; ++r) p1[r] = __builtin_amdgcn_exp2f(p1[r]);
;   float ps = 0;
; #pragma unroll
;   for (int r = 0; r < 16; ++r) ps += p0[r];
; #pragma unroll
;   for (int r = 0; r < 16; ++r) ps += p1[r];
;   { auto rr = __builtin_amdgcn_permlane32_swap(__float_as_uint(ps), __float_as_uint(ps), false, false);
;     ps = __uint_as_float(rr[0]) + __uint_as_float(rr[1]); }
;   l_reg = l_reg * alpha + ps;
;     ...
;   PK4(p0, 0, pa0); PK4(p0, 8, pa1); PK4(p1, 0, pa2); PK4(p1, 8, pa3);
;     ...
; }
; __device__ __forceinline__ void qkt(f32x16& p0, f32x16& p1, const char* Ks, const bf16x8* qr, const char* qrl, int r32, int hi) {
;   p0 = f32x16{}; p1 = f32x16{};
; #pragma unroll
;   for (int d0 = 0; d0 < 8; ++d0) { int cb = (d0 * 16 + hi * 8) * 2;
;     bf16x8 b0 = *reinterpret_cast<const bf16x8*>(Ks + KSWZ(r32, cb));
;     bf16x8 b1 = *reinterpret_cast<const bf16x8*>(Ks + KSWZ(32 + r32, cb));
;     p0 = __builtin_amdgcn_mfma_f32_32x32x16_bf16(b0, qr[d0], p0, 0, 0, 0);
;     p1 = __builtin_amdgcn_mfma_f32_32x32x16_bf16(b1, qr[d0], p1, 0, 0, 0); }
; #pragma unroll
;   for (int d0 = 8; d0 < 12; ++d0) { int cb = (d0 * 16 + hi * 8) * 2;
;     bf16x8 b0 = *reinterpret_cast<const bf16x8*>(Ks + KSWZ(r32, cb));
;     bf16x8 b1 = *reinterpret_cast<const bf16x8*>(Ks + KSWZ(32 + r32, cb));
;     bf16x8 qf = *reinterpret_cast<const bf16x8*>(qrl + (((2 * (d0 - 8) + hi) ^ ((r32 >> 1) & 7)) << 4));
;     p0 = __builtin_amdgcn_mfma_f32_32x32x16_bf16(b0, qf, p0, 0, 0, 0);
;     p1 = __builtin_amdgcn_mfma_f32_32x32x16_bf16(b1, qf, p1, 0, 0, 0); }
; }
.Lattn_steady:
	s_sub_i32 s30, s76, 1
	s_cmp_eq_u32 s76, 0
	s_cselect_b32 s30, 2, s30
	s_add_i32 s18, s76, 1
	s_cmp_lg_u32 s76, 2
	s_cselect_b32 s18, s18, 0
	v_exp_f32_e32 v225, v225
	v_exp_f32_e32 v228, v228
	v_exp_f32_e32 v226, v226
	v_add_f32_e32 v211, v225, v228
	s_waitcnt lgkmcnt(2)
	v_mfma_f32_32x32x16_bf16 v[80:95], v[232:235], v[124:127], 0
	ds_read_b128 v[232:235], v206 offset:36864
	v_exp_f32_e32 v229, v229
	v_add_f32_e32 v211, v226, v211
	v_exp_f32_e32 v227, v227
	v_mfma_f32_32x32x16_bf16 v[64:79], v[236:239], v[124:127], 0
	ds_read_b128 v[236:239], v206 offset:49152
	v_add_f32_e32 v211, v229, v211
	v_exp_f32_e32 v230, v230
	v_add_f32_e32 v211, v227, v211
	s_waitcnt lgkmcnt(2)
	v_mfma_f32_32x32x16_bf16 v[80:95], v[240:243], v[120:123], v[80:95]
	ds_read_b128 v[240:243], v208 offset:36864
	v_exp_f32_e32 v223, v223
	v_add_f32_e32 v211, v230, v211
	v_exp_f32_e32 v224, v224
	v_mfma_f32_32x32x16_bf16 v[64:79], v[248:251], v[120:123], v[64:79]
	ds_read_b128 v[248:251], v208 offset:49152
	v_add_f32_e32 v211, v223, v211
	v_exp_f32_e32 v219, v219
	v_add_f32_e32 v211, v224, v211
	s_waitcnt lgkmcnt(2)
	v_mfma_f32_32x32x16_bf16 v[80:95], v[232:235], v[116:119], v[80:95]
	ds_read_b128 v[232:235], v207 offset:36864
	v_exp_f32_e32 v221, v221
	v_add_f32_e32 v211, v219, v211
	v_exp_f32_e32 v220, v220
	v_mfma_f32_32x32x16_bf16 v[64:79], v[236:239], v[116:119], v[64:79]
	ds_read_b128 v[236:239], v207 offset:49152
	v_add_f32_e32 v211, v221, v211
	v_exp_f32_e32 v222, v222
	v_add_f32_e32 v211, v220, v211
	s_waitcnt lgkmcnt(2)
	v_mfma_f32_32x32x16_bf16 v[80:95], v[240:243], v[112:115], v[80:95]
	ds_read_b128 v[240:243], v204 offset:36864
	v_exp_f32_e32 v215, v215
	v_add_f32_e32 v211, v222, v211
	v_exp_f32_e32 v217, v217
	v_mfma_f32_32x32x16_bf16 v[64:79], v[248:251], v[112:115], v[64:79]
	ds_read_b128 v[248:251], v204 offset:49152
	v_add_f32_e32 v211, v215, v211
	v_exp_f32_e32 v216, v216
	v_add_f32_e32 v211, v217, v211
	s_waitcnt lgkmcnt(2)
	v_mfma_f32_32x32x16_bf16 v[80:95], v[232:235], v[108:111], v[80:95]
	ds_read_b128 v[232:235], v203 offset:36864
	v_exp_f32_e32 v218, v218
	v_add_f32_e32 v211, v216, v211
	v_exp_f32_e32 v162, v162
	v_mfma_f32_32x32x16_bf16 v[64:79], v[236:239], v[108:111], v[64:79]
	ds_read_b128 v[236:239], v203 offset:49152
	v_add_f32_e32 v211, v218, v211
	v_exp_f32_e32 v163, v163
	v_exp_f32_e32 v160, v160
	s_waitcnt lgkmcnt(2)
	v_mfma_f32_32x32x16_bf16 v[80:95], v[240:243], v[104:107], v[80:95]
	ds_read_b128 v[240:243], v200 offset:36864
	v_exp_f32_e32 v161, v161
	v_exp_f32_e32 v158, v158
	v_mfma_f32_32x32x16_bf16 v[64:79], v[248:251], v[104:107], v[64:79]
	ds_read_b128 v[248:251], v200 offset:49152
	v_exp_f32_e32 v159, v159
	v_exp_f32_e32 v156, v156
	s_waitcnt lgkmcnt(2)
	v_mfma_f32_32x32x16_bf16 v[80:95], v[232:235], v[100:103], v[80:95]
	ds_read_b128 v[232:235], v191 offset:36864
	v_exp_f32_e32 v157, v157
	v_exp_f32_e32 v154, v154
	v_mfma_f32_32x32x16_bf16 v[64:79], v[236:239], v[100:103], v[64:79]
	ds_read_b128 v[236:239], v202 offset:49152
	v_exp_f32_e32 v155, v155
	v_exp_f32_e32 v152, v152
	s_waitcnt lgkmcnt(2)
	v_mfma_f32_32x32x16_bf16 v[80:95], v[240:243], v[96:99], v[80:95]
	ds_read_b128 v[240:243], v182
	v_exp_f32_e32 v153, v153
	v_exp_f32_e32 v150, v150
	v_mfma_f32_32x32x16_bf16 v[64:79], v[248:251], v[96:99], v[64:79]
	ds_read_b128 v[248:251], v198 offset:36864
	v_exp_f32_e32 v151, v151
	v_exp_f32_e32 v148, v148
	s_waitcnt lgkmcnt(1)
	v_mfma_f32_32x32x16_bf16 v[80:95], v[232:235], v[240:243], v[80:95]
	ds_read_b128 v[232:235], v201 offset:49152
	v_exp_f32_e32 v149, v149
	v_add_f32_e32 v212, v162, v163
	v_add_f32_e32 v212, v160, v212
	v_add_f32_e32 v212, v161, v212
	v_mfma_f32_32x32x16_bf16 v[64:79], v[236:239], v[240:243], v[64:79]
	ds_read_b128 v[236:239], v181
	ds_read_b128 v[240:243], v187 offset:36864
	v_add_f32_e32 v212, v158, v212
	v_add_f32_e32 v212, v159, v212
	v_add_f32_e32 v212, v156, v212
	v_add_f32_e32 v212, v157, v212
	v_add_f32_e32 v212, v154, v212
	s_waitcnt lgkmcnt(1)
	v_mfma_f32_32x32x16_bf16 v[80:95], v[248:251], v[236:239], v[80:95]
	ds_read_b128 v[248:251], v189 offset:49152
	v_add_f32_e32 v212, v155, v212
	v_add_f32_e32 v212, v152, v212
	v_add_f32_e32 v212, v153, v212
	v_add_f32_e32 v212, v150, v212
	v_add_f32_e32 v212, v151, v212
	v_mfma_f32_32x32x16_bf16 v[64:79], v[232:235], v[236:239], v[64:79]
	ds_read_b128 v[232:235], v179
	ds_read_b128 v[236:239], v188 offset:36864
	v_add_f32_e32 v212, v148, v212
	v_add_f32_e32 v212, v149, v212
	v_add_f32_e32 v211, v211, v212
	v_mov_b32_e32 v212, v211
	s_lshl_b32 s19, s18, 14
	v_add_u32_e32 v231, s19, v183
	s_waitcnt vmcnt(0)
; __device__ __forceinline__ void finishSM(f32x16& p0, f32x16& p1, float alpha, float& l_reg, bf16x8& pa0, bf16x8& pa1, bf16x8& pa2, bf16x8& pa3) {
;     ...
;   PK4(p0, 0, pa0); PK4(p0, 8, pa1); PK4(p1, 0, pa2); PK4(p1, 8, pa3);
;     ...
; }
; __device__ __forceinline__ void qkt(f32x16& p0, f32x16& p1, const char* Ks, const bf16x8* qr, const char* qrl, int r32, int hi) {
;   p0 = f32x16{}; p1 = f32x16{};
; #pragma unroll
;   for (int d0 = 0; d0 < 8; ++d0) { int cb = (d0 * 16 + hi * 8) * 2;
;     bf16x8 b0 = *reinterpret_cast<const bf16x8*>(Ks + KSWZ(r32, cb));
;     bf16x8 b1 = *reinterpret_cast<const bf16x8*>(Ks + KSWZ(32 + r32, cb));
;     p0 = __builtin_amdgcn_mfma_f32_32x32x16_bf16(b0, qr[d0], p0, 0, 0, 0);
;     p1 = __builtin_amdgcn_mfma_f32_32x32x16_bf16(b1, qr[d0], p1, 0, 0, 0); }
; #pragma unroll
;   for (int d0 = 8; d0 < 12; ++d0) { int cb = (d0 * 16 + hi * 8) * 2;
;     bf16x8 b0 = *reinterpret_cast<const bf16x8*>(Ks + KSWZ(r32, cb));
;     bf16x8 b1 = *reinterpret_cast<const bf16x8*>(Ks + KSWZ(32 + r32, cb));
;     bf16x8 qf = *reinterpret_cast<const bf16x8*>(qrl + (((2 * (d0 - 8) + hi) ^ ((r32 >> 1) & 7)) << 4));
;     p0 = __builtin_amdgcn_mfma_f32_32x32x16_bf16(b0, qf, p0, 0, 0, 0);
;     p1 = __builtin_amdgcn_mfma_f32_32x32x16_bf16(b1, qf, p1, 0, 0, 0); }
; }
; __device__ __forceinline__ int v_st(int k, int c) { const int kk = (k & ~0xC) | ((k & 4) << 1) | ((k & 8) >> 1); return ((kk >> 3) * 4 + (c >> 5)) * 512 + ((kk & 7) * 32 + (c & 31)) * 2; }
; __device__ __forceinline__ int v_rd_base(int lane) { return ((lane & 3) << 3) | (((lane >> 2) & 3) << 6) | (((lane >> 4) & 1) << 5) | (((lane >> 5) & 1) << 8); }
; template <int OFF> __device__ __forceinline__ s16x4 tr_read(int vb) {
;   s16x4 r; asm volatile("ds_read_b64_tr_b16 %0, %1 offset:%2" : "=&v"(r) : "v"(vb), "i"(OFF) : "memory"); return r;
; }
; template <int D0> __device__ __forceinline__ void pv_one(f32x16& od, int vb, bf16x8 pa0, bf16x8 pa1, bf16x8 pa2, bf16x8 pa3) {
;   const s16x4 l0 = tr_read<v_rd_off(D0, 0, 0)>(vb), h0 = tr_read<v_rd_off(D0, 0, 1)>(vb), l1 = tr_read<v_rd_off(D0, 1, 0)>(vb), h1 = tr_read<v_rd_off(D0, 1, 1)>(vb);
;   const s16x4 l2 = tr_read<v_rd_off(D0, 2, 0)>(vb), h2 = tr_read<v_rd_off(D0, 2, 1)>(vb), l3 = tr_read<v_rd_off(D0, 3, 0)>(vb), h3 = tr_read<v_rd_off(D0, 3, 1)>(vb);
;   asm volatile("s_waitcnt lgkmcnt(0)" ::: "memory"); SBAR();
	s_waitcnt lgkmcnt(1)
	v_mfma_f32_32x32x16_bf16 v[80:95], v[240:243], v[232:235], v[80:95]
	ds_read_b128 v[240:243], v190 offset:49152
	ds_write_b128 v231, v[140:143]
	v_add_u32_e32 v140, s19, v184
	ds_write_b128 v140, v[144:147]
	ds_write_b128 v185, v[136:139] offset:12288
	ds_write_b128 v185, v[132:135] offset:24576
	s_mov_b32 s18, 0xfffa0000
	ds_write_b128 v186, v[128:131] offset:12288
	v_mfma_f32_32x32x16_bf16 v[64:79], v[248:251], v[232:235], v[64:79]
	ds_read_b128 v[248:251], v177
	v_add_co_u32_e32 v128, vcc, s18, v168
	s_mov_b32 s18, 0xfffc0000
	s_nop 0
	v_addc_co_u32_e32 v129, vcc, -1, v169, vcc
	v_add_co_u32_e32 v130, vcc, s18, v168
	s_movk_i32 s18, 0xe000
	s_nop 0
	v_addc_co_u32_e32 v131, vcc, -1, v169, vcc
	global_load_dwordx4 v[140:143], v[128:129], off
	s_waitcnt lgkmcnt(0)
	v_mfma_f32_32x32x16_bf16 v[80:95], v[236:239], v[248:251], v[80:95]
	global_load_dwordx4 v[136:139], v[128:129], off offset:-256
	global_load_dwordx4 v[144:147], v[130:131], off
	global_load_dwordx4 v[132:135], v[130:131], off offset:-256
	v_add_co_u32_e32 v128, vcc, s18, v166
	s_nop 1
	v_addc_co_u32_e32 v129, vcc, -1, v167, vcc
	v_mfma_f32_32x32x16_bf16 v[64:79], v[240:243], v[248:251], v[64:79]
	global_load_dwordx4 v[128:131], v[128:129], off
	v_cvt_pk_bf16_f32 v158, v158, v159
	v_cvt_pk_bf16_f32 v159, v156, v157
	v_permlane32_swap_b32_e32 v211, v212
	v_cvt_pk_bf16_f32 v156, v162, v163
	s_lshl_b32 s31, s30, 14
	v_add_u32_e32 v180, s31, v178
	ds_read_b64_tr_b16 v[232:233], v180 offset:0
	ds_read_b64_tr_b16 v[234:235], v180 offset:2048
	ds_read_b64_tr_b16 v[236:237], v180 offset:512
	ds_read_b64_tr_b16 v[238:239], v180 offset:2560
	ds_read_b64_tr_b16 v[240:241], v180 offset:1024
	ds_read_b64_tr_b16 v[242:243], v180 offset:3072
	ds_read_b64_tr_b16 v[248:249], v180 offset:1536
	ds_read_b64_tr_b16 v[250:251], v180 offset:3584
	v_cvt_pk_bf16_f32 v157, v160, v161
	v_cvt_pk_bf16_f32 v160, v154, v155
	v_cvt_pk_bf16_f32 v161, v152, v153
	v_cvt_pk_bf16_f32 v162, v150, v151
	v_cvt_pk_bf16_f32 v163, v148, v149
	v_add_f32_e32 v211, v211, v212
	v_cvt_pk_bf16_f32 v148, v225, v228
	v_cvt_pk_bf16_f32 v149, v226, v229
	v_cvt_pk_bf16_f32 v150, v227, v230
	v_cvt_pk_bf16_f32 v151, v223, v224
	v_cvt_pk_bf16_f32 v152, v219, v221
	v_cvt_pk_bf16_f32 v153, v220, v222
	v_cvt_pk_bf16_f32 v154, v215, v217
	v_cvt_pk_bf16_f32 v155, v216, v218
	v_fma_f32 v176, v209, v176, v211
	s_nop 3
	v_max3_f32 v194, v80, v81, v82
	v_max3_f32 v195, v64, v65, v66
	v_max3_f32 v194, v194, v83, v84
	v_max3_f32 v195, v195, v67, v68
	v_max3_f32 v194, v194, v85, v86
	s_waitcnt lgkmcnt(4)
	v_mfma_f32_32x32x16_bf16 v[32:47], v[148:151], v[232:235], v[32:47]
	ds_read_b64_tr_b16 v[232:233], v180 offset:4096
	ds_read_b64_tr_b16 v[234:235], v180 offset:6144
	v_max3_f32 v195, v195, v69, v70
	v_max3_f32 v194, v194, v87, v88
	v_max3_f32 v195, v195, v71, v72
	v_max3_f32 v194, v194, v89, v90
	v_max3_f32 v195, v195, v73, v74
	v_mfma_f32_32x32x16_bf16 v[48:63], v[148:151], v[236:239], v[48:63]
	ds_read_b64_tr_b16 v[236:237], v180 offset:4608
	ds_read_b64_tr_b16 v[238:239], v180 offset:6656
	v_max3_f32 v194, v194, v91, v92
	v_max3_f32 v195, v195, v75, v76
	v_max3_f32 v194, v194, v93, v94
	v_max3_f32 v195, v195, v77, v78
	v_max3_f32 v194, v194, v95, v195
	s_waitcnt lgkmcnt(4)
	v_mfma_f32_32x32x16_bf16 v[16:31], v[148:151], v[240:243], v[16:31]
	ds_read_b64_tr_b16 v[240:241], v180 offset:5120
	ds_read_b64_tr_b16 v[242:243], v180 offset:7168
	v_max_f32_e32 v194, v194, v79
	v_mov_b32_e32 v195, v194
	s_nop 1
	v_permlane32_swap_b32_e32 v194, v195
	v_max_f32_e32 v194, v194, v195
	v_mfma_f32_32x32x16_bf16 v[0:15], v[148:151], v[248:251], v[0:15]
	ds_read_b64_tr_b16 v[248:249], v180 offset:5632
	ds_read_b64_tr_b16 v[250:251], v180 offset:7680
	v_sub_f32_e32 v195, v194, v210
	v_cmp_ge_f32_e32 vcc, s15, v195
	s_cmp_eq_u64 vcc, exec
	s_cselect_b64 s[40:41], -1, 0
	s_cbranch_scc1 .Lattn_fast1
	v_max_f32_e32 v194, v210, v194
	v_sub_f32_e32 v195, v210, v194
	v_mul_f32_e32 v195, 0x3dd53b94, v195
	v_exp_f32_e32 v214, v195
	v_mov_b32_e32 v210, v194
	s_branch .Lattn_join1
